# mixer-C loop MFMA issue order: accumulator chains (QK 4 deep, PV 2 deep) with snake sharing of K/V/P fragments; on top of the GEMM snake order
# speedup vs baseline: 1.0084x; 1.0000x over previous
; __device__ __forceinline__ void attn_c_unit(LAS unsigned char* lds, const bf16_t* proj, const bf16_t* vt, bf16_t* obuf, int b, int hk, int blk, float mref, unsigned long long* sg) {
;     ...
;     const int qhead = 4 * hk + (w >> 1), qpos = blk * 128 + 64 * (w & 1) + r, qcol = QC_OFF + 64 * qhead, kcol = KC_OFF + 64 * hk, vslot = 10 + hk, ocol = 1024 + 64 * qhead;
;     const size_t tokbase = (size_t)b * SEQ;
;     const int srow = tid >> 3, sch = tid & 7;
;     const bf16_t* kg = proj + (tokbase + srow) * INW + kcol + sch * 8;
;     const bf16_t* vg = vt + ((size_t)(b * NVS + vslot) * 64 + srow) * SEQ + sch * 8;
;     const unsigned sdst = srow * KP + sch * 16;
;     u32x4 kreg, vreg;
;     const bf16_t* qg = proj + (tokbase + qpos) * INW + qcol + 8 * h;
;     bf16x8 qf[2][4];
; #pragma unroll
;     for (int j = 0; j < 2; ++j)
; #pragma unroll
;         for (int ks = 0; ks < 4; ++ks) qf[j][ks] = *(const bf16x8*)(qg + (size_t)(32 * j) * INW + 16 * ks);
;     f32x16 negm;
; #pragma unroll
;     for (int i = 0; i < 16; ++i) negm[i] = 0.f;
;     float l0 = 0.f, l1 = 0.f;
;     f32x16 o00, o01, o10, o11;
; #pragma unroll
;     for (int i = 0; i < 16; ++i) { o00[i] = 0.f; o01[i] = 0.f; o10[i] = 0.f; o11[i] = 0.f; }
;     const int pr = (r & ~12) | ((r & 4) << 1) | ((r & 8) >> 1);
;     constexpr int nT = SEQ / 64;
;     constexpr int CK = 0, CV = 4 * ATT_TILE;
; #pragma unroll
;     for (int i = 0; i < 2; ++i) { kreg = *(const u32x4*)(kg + (size_t)(i * 64) * INW); vreg = *(const u32x4*)(vg + i * 64);
;         *(LAS u32x4*)(lds + CK + i * ATT_TILE + sdst) = kreg; *(LAS u32x4*)(lds + CV + i * ATT_TILE + sdst) = vreg; }
;     __syncthreads();
;     for (int it = 0; it < nT; ++it) {
;         const int buf = it & 3;
;         if (it + 2 < nT) { kreg = *(const u32x4*)(kg + (size_t)((it + 2) * 64) * INW); vreg = *(const u32x4*)(vg + (it + 2) * 64); }
;         const LAS unsigned char* kb = lds + CK + buf * ATT_TILE + pr * KP + 16 * h;
;         f32x16 s00, s01, s10, s11;
;         {
;             const bf16x8 a0 = *(const LAS bf16x8*)(kb), a1 = *(const LAS bf16x8*)(kb + 32 * KP);
;             s00 = __builtin_amdgcn_mfma_f32_32x32x16_bf16(a0, qf[0][0], negm, 0, 0, 0);
;             s10 = __builtin_amdgcn_mfma_f32_32x32x16_bf16(a0, qf[1][0], negm, 0, 0, 0);
;             s01 = __builtin_amdgcn_mfma_f32_32x32x16_bf16(a1, qf[0][0], negm, 0, 0, 0);
.LBB0_207:
	s_bfe_u32 s24, s11, 0x10002
	v_mov_b32_e32 v18, v199
	s_lshl_b32 s54, s24, 13
	v_ashrrev_i32_e32 v8, 3, v18
	v_add_u32_e32 v0, s54, v8
	v_mov_b64_e32 v[10:11], s[86:87]
	s_and_b32 s22, s11, 3
	s_waitcnt lgkmcnt(0)
	v_mad_i64_i32 v[0:1], s[12:13], v0, s25, v[10:11]
	s_mul_i32 s14, s24, 14
	s_lshl_b32 s12, s22, 7
	s_mov_b32 s13, s55
	v_lshlrev_b32_e32 v4, 4, v18
	s_add_i32 s15, s22, s14
	v_lshl_add_u64 v[0:1], v[0:1], 0, s[12:13]
	v_and_b32_e32 v128, 0x70, v4
	s_lshl_b32 s12, s15, 6
	v_lshl_add_u64 v[14:15], v[0:1], 0, v[128:129]
	v_ashrrev_i32_e32 v9, 31, v8
	s_addk_i32 s12, 0x280
	v_add_co_u32_e32 v0, vcc, s48, v14
	v_lshl_add_u64 v[2:3], s[12:13], 0, v[8:9]
	s_nop 0
	v_addc_co_u32_e32 v1, vcc, 0, v15, vcc
	s_mov_b32 s12, 0x79000
	v_add_co_u32_e32 v14, vcc, s12, v14
	s_and_b32 s12, s10, 3
	s_add_i32 s14, s14, s12
	s_lshl_b32 s13, s14, 6
	s_add_i32 s14, s13, 0x280
	s_lshl_b32 s26, s12, 7
	v_readfirstlane_b32 s12, v18
	s_lshl_b32 s13, s11, 4
	s_and_b32 s13, s13, 0xffffff80
	s_and_b32 s23, s12, 64
	v_and_b32_e32 v19, 31, v18
	s_or_b32 s13, s13, s23
	v_lshlrev_b64 v[2:3], 14, v[2:3]
	v_or_b32_e32 v182, s13, v19
	v_lshl_add_u64 v[2:3], s[84:85], 0, v[2:3]
	v_addc_co_u32_e32 v15, vcc, 0, v15, vcc
	s_ashr_i32 s12, s12, 1
	v_ashrrev_i32_e32 v183, 31, v182
	v_lshl_add_u64 v[12:13], v[2:3], 0, v[128:129]
	global_load_dwordx4 v[0:3], v[0:1], off offset:2560
	s_nop 0
	global_load_dwordx4 v[4:7], v[12:13], off
	global_load_dwordx4 v[130:133], v[14:15], off offset:2560
	global_load_dwordx4 v[134:137], v[12:13], off offset:128
	s_lshl_b32 s13, s22, 8
	s_andn2_b32 s12, s12, 63
	v_lshl_add_u64 v[184:185], v[182:183], 0, s[54:55]
	s_add_i32 s12, s12, s13
	v_mad_u64_u32 v[10:11], s[22:23], v184, s25, v[10:11]
	v_bfe_u32 v196, v18, 5, 1
	v_mad_i32_i24 v11, v185, s25, v11
	s_ashr_i32 s13, s12, 31
	v_lshl_add_u64 v[10:11], s[12:13], 1, v[10:11]
	v_lshlrev_b32_e32 v12, 4, v196
	v_mov_b32_e32 v13, v129
	v_lshl_add_u64 v[10:11], v[10:11], 0, v[12:13]
	s_mov_b64 s[22:23], 0x1200
	v_add_co_u32_e32 v16, vcc, s48, v10
	v_lshl_add_u64 v[14:15], v[10:11], 0, s[22:23]
	s_nop 0
	v_addc_co_u32_e32 v17, vcc, 0, v11, vcc
	s_mov_b32 s23, 0x3d000
	v_add_co_u32_e32 v10, vcc, s23, v10
	global_load_dwordx4 v[138:141], v[14:15], off offset:32
	global_load_dwordx4 v[142:145], v[14:15], off offset:64
	global_load_dwordx4 v[146:149], v[16:17], off offset:512
	global_load_dwordx4 v[150:153], v[14:15], off offset:96
	v_addc_co_u32_e32 v11, vcc, 0, v11, vcc
	global_load_dwordx4 v[154:157], v[10:11], off offset:512
	global_load_dwordx4 v[158:161], v[10:11], off offset:544
	global_load_dwordx4 v[162:165], v[10:11], off offset:576
	global_load_dwordx4 v[166:169], v[10:11], off offset:608
	v_mul_lo_u32 v10, v8, s16
	v_lshlrev_b32_e32 v11, 1, v18
	v_lshrrev_b32_e32 v13, 1, v18
	v_add3_u32 v197, v10, v128, 0
	v_and_b32_e32 v11, 8, v11
	v_and_b32_e32 v13, 4, v13
	s_mov_b32 s15, s55
	v_mov_b32_e32 v32, 0
	s_mov_b32 s22, 0
	v_mov_b32_e32 v33, v32
	v_mov_b32_e32 v34, v32
	v_mov_b32_e32 v35, v32
	v_mov_b32_e32 v36, v32
	v_mov_b32_e32 v37, v32
	v_mov_b32_e32 v38, v32
	s_waitcnt vmcnt(11)
	ds_write_b128 v197, v[0:3]
	s_waitcnt vmcnt(10)
	ds_write_b128 v197, v[4:7] offset:36864
	s_waitcnt vmcnt(9)
	ds_write_b128 v197, v[130:133] offset:9216
	s_waitcnt vmcnt(8)
	ds_write_b128 v197, v[134:137] offset:46080
	v_and_b32_e32 v0, 19, v18
	v_or3_b32 v0, v0, v11, v13
	v_mul_u32_u24_e32 v0, 0x90, v0
	v_add3_u32 v198, 0, v0, v12
	v_mul_u32_u24_e32 v0, 0x90, v19
	v_add3_u32 v200, 0, v0, v12
	v_lshl_add_u64 v[0:1], v[8:9], 0, s[14:15]
	v_lshlrev_b64 v[0:1], 14, v[0:1]
	v_or_b32_e32 v0, v0, v128
	v_lshl_add_u64 v[186:187], s[4:5], 0, v[0:1]
	v_mad_i64_i32 v[0:1], s[14:15], v8, s25, 0
	v_mad_u64_u32 v[0:1], s[14:15], s24, v222, v[0:1]
	v_or3_b32 v0, v0, s26, v128
	v_lshl_add_u64 v[188:189], s[6:7], 0, v[0:1]
	v_mov_b32_e32 v39, v32
	v_mov_b32_e32 v40, v32
	v_mov_b32_e32 v41, v32
	v_mov_b32_e32 v42, v32
	v_mov_b32_e32 v43, v32
	v_mov_b32_e32 v44, v32
	v_mov_b32_e32 v45, v32
	v_mov_b32_e32 v46, v32
	v_mov_b32_e32 v47, v32
	v_mov_b32_e32 v48, v32
	v_mov_b32_e32 v49, v32
	v_mov_b32_e32 v50, v32
	v_mov_b32_e32 v51, v32
	v_mov_b32_e32 v52, v32
	v_mov_b32_e32 v53, v32
	v_mov_b32_e32 v54, v32
	v_mov_b32_e32 v55, v32
	v_mov_b32_e32 v56, v32
	v_mov_b32_e32 v57, v32
	v_mov_b32_e32 v58, v32
	v_mov_b32_e32 v59, v32
	v_mov_b32_e32 v60, v32
	v_mov_b32_e32 v61, v32
	v_mov_b32_e32 v62, v32
	v_mov_b32_e32 v63, v32
	v_mov_b32_e32 v0, v32
	v_mov_b32_e32 v1, v32
	v_mov_b32_e32 v2, v32
	v_mov_b32_e32 v3, v32
	v_mov_b32_e32 v4, v32
	v_mov_b32_e32 v5, v32
	v_mov_b32_e32 v6, v32
	v_mov_b32_e32 v7, v32
	v_mov_b32_e32 v8, v32
	v_mov_b32_e32 v9, v32
	v_mov_b32_e32 v10, v32
	v_mov_b32_e32 v11, v32
	v_mov_b32_e32 v12, v32
	v_mov_b32_e32 v13, v32
	v_mov_b32_e32 v14, v32
	v_mov_b32_e32 v15, v32
	v_mov_b32_e32 v16, v32
	v_mov_b32_e32 v17, v32
	v_mov_b32_e32 v18, v32
	v_mov_b32_e32 v19, v32
	v_mov_b32_e32 v20, v32
	v_mov_b32_e32 v21, v32
	v_mov_b32_e32 v22, v32
	v_mov_b32_e32 v23, v32
	v_mov_b32_e32 v24, v32
	v_mov_b32_e32 v25, v32
	v_mov_b32_e32 v26, v32
	v_mov_b32_e32 v27, v32
	v_mov_b32_e32 v28, v32
	v_mov_b32_e32 v29, v32
	v_mov_b32_e32 v30, v32
	v_mov_b32_e32 v31, v32
	v_mov_b32_e32 v190, v32
	v_mov_b32_e32 v191, v32
	s_waitcnt vmcnt(0) lgkmcnt(0)
	s_barrier
	ds_read_b128 v[226:229], v198 offset:0
	ds_read_b128 v[230:233], v198 offset:32
	ds_read_b128 v[234:237], v198 offset:64
	ds_read_b128 v[238:241], v198 offset:96
	ds_read_b128 v[202:205], v200 offset:36928
	ds_read_b128 v[192:195], v200 offset:41536
	ds_read_b128 v[210:213], v200 offset:36960
	ds_read_b128 v[242:245], v200 offset:41568
	v_mov_b32_e32 v214, 0
	v_mov_b32_e32 v215, 0
	v_mov_b32_e32 v96, 0
	v_mov_b32_e32 v97, 0
	v_mov_b32_e32 v98, 0
	v_mov_b32_e32 v99, 0
	v_mov_b32_e32 v100, 0
	v_mov_b32_e32 v101, 0
	v_mov_b32_e32 v102, 0
	v_mov_b32_e32 v103, 0
	v_mov_b32_e32 v112, 0
	v_mov_b32_e32 v113, 0
	v_mov_b32_e32 v114, 0
	v_mov_b32_e32 v115, 0
	v_mov_b32_e32 v116, 0
	v_mov_b32_e32 v117, 0
	v_mov_b32_e32 v118, 0
	v_mov_b32_e32 v119, 0
	v_mov_b32_e32 v128, v198
	s_waitcnt lgkmcnt(4)
	v_mfma_f32_32x32x16_bf16 v[64:79], v[226:229], v[146:149], 0
	v_mfma_f32_32x32x16_bf16 v[64:79], v[230:233], v[138:141], v[64:79]
	v_mfma_f32_32x32x16_bf16 v[64:79], v[234:237], v[142:145], v[64:79]
	v_mfma_f32_32x32x16_bf16 v[64:79], v[238:241], v[150:153], v[64:79]
	v_mfma_f32_32x32x16_bf16 v[80:95], v[238:241], v[166:169], 0
	ds_read_b128 v[238:241], v128 offset:4704
	v_mfma_f32_32x32x16_bf16 v[80:95], v[234:237], v[162:165], v[80:95]
	ds_read_b128 v[234:237], v128 offset:4672
	v_mfma_f32_32x32x16_bf16 v[80:95], v[230:233], v[158:161], v[80:95]
	ds_read_b128 v[230:233], v128 offset:4640
	v_mfma_f32_32x32x16_bf16 v[80:95], v[226:229], v[154:157], v[80:95]
	ds_read_b128 v[226:229], v128 offset:4608
	s_nop 7

; #define LAS __attribute__((address_space(3)))
; __device__ __forceinline__ unsigned pk_bf16(float lo, float hi) { return pg8::cvt_pk_bf16(lo, hi); }
; __device__ __forceinline__ void attn_c_unit(LAS unsigned char* lds, const bf16_t* proj, const bf16_t* vt, bf16_t* obuf, int b, int hk, int blk, float mref, unsigned long long* sg) {
;     ...
;         u32x4 pw0[4], pw1[4];
;         {
;             float ps = 0.f;
; #pragma unroll
;             for (int i = 0; i < 16; ++i) { s00[i] = __builtin_amdgcn_exp2f(s00[i]); s01[i] = __builtin_amdgcn_exp2f(s01[i]); ps += s00[i] + s01[i]; }
;             l0 += ps;
; #pragma unroll
;             for (int q = 0; q < 4; ++q) { pw0[0][q] = pk_bf16(s00[2 * q], s00[2 * q + 1]); pw0[1][q] = pk_bf16(s00[8 + 2 * q], s00[8 + 2 * q + 1]);
;                                           pw0[2][q] = pk_bf16(s01[2 * q], s01[2 * q + 1]); pw0[3][q] = pk_bf16(s01[8 + 2 * q], s01[8 + 2 * q + 1]); }
;         }
;         {
;             float ps = 0.f;
; #pragma unroll
;             for (int i = 0; i < 16; ++i) { s10[i] = __builtin_amdgcn_exp2f(s10[i]); s11[i] = __builtin_amdgcn_exp2f(s11[i]); ps += s10[i] + s11[i]; }
;             l1 += ps;
; #pragma unroll
;             for (int q = 0; q < 4; ++q) { pw1[0][q] = pk_bf16(s10[2 * q], s10[2 * q + 1]); pw1[1][q] = pk_bf16(s10[8 + 2 * q], s10[8 + 2 * q + 1]);
;                                           pw1[2][q] = pk_bf16(s11[2 * q], s11[2 * q + 1]); pw1[3][q] = pk_bf16(s11[8 + 2 * q], s11[8 + 2 * q + 1]); }
;         }
;         const LAS unsigned char* vb = lds + CV + buf * ATT_TILE + r * KP + 16 * h;
; #pragma unroll
;         for (int ks = 0; ks < 4; ++ks) {
;             const bf16x8 a0 = *(const LAS bf16x8*)(vb + 32 * ks), a1 = *(const LAS bf16x8*)(vb + 32 * KP + 32 * ks);
;             const bf16x8 p0 = __builtin_bit_cast(bf16x8, pw0[ks]), p1 = __builtin_bit_cast(bf16x8, pw1[ks]);
;             o00 = __builtin_amdgcn_mfma_f32_32x32x16_bf16(a0, p0, o00, 0, 0, 0);
;             o10 = __builtin_amdgcn_mfma_f32_32x32x16_bf16(a0, p1, o10, 0, 0, 0);
;             o01 = __builtin_amdgcn_mfma_f32_32x32x16_bf16(a1, p0, o01, 0, 0, 0);
;             o11 = __builtin_amdgcn_mfma_f32_32x32x16_bf16(a1, p1, o11, 0, 0, 0);
;         }
;         if (it + 2 < nT) { *(LAS u32x4*)(lds + CK + (buf ^ 2) * ATT_TILE + sdst) = kreg; *(LAS u32x4*)(lds + CV + (buf ^ 2) * ATT_TILE + sdst) = vreg; }
.Lc_noload:
	v_exp_f32_e32 v64, v64
	v_exp_f32_e32 v65, v65
	v_exp_f32_e32 v66, v66
	v_exp_f32_e32 v67, v67
	v_add_f32_e32 v190, v190, v64
	v_mfma_f32_32x32x16_bf16 v[32:47], v[210:213], v[100:103], v[32:47]
	s_and_b32 s24, s22, 7
	s_mulk_i32 s24, 0x2400
	v_add_f32_e32 v214, v214, v65
	v_cvt_pk_bf16_f32 v64, v64, v65
	v_exp_f32_e32 v68, v68
	v_exp_f32_e32 v69, v69
	v_add_f32_e32 v190, v190, v66
	v_mfma_f32_32x32x16_bf16 v[0:15], v[210:213], v[116:119], v[0:15]
	v_add_u32_e32 v246, s24, v200
	v_add_f32_e32 v214, v214, v67
	v_cvt_pk_bf16_f32 v65, v66, v67
	v_exp_f32_e32 v70, v70
	v_exp_f32_e32 v71, v71
	v_add_f32_e32 v190, v190, v68
	v_mfma_f32_32x32x16_bf16 v[0:15], v[202:205], v[112:115], v[0:15]
	v_lshl_add_u64 v[186:187], v[186:187], 0, s[64:65]
	v_add_f32_e32 v214, v214, v69
	v_cvt_pk_bf16_f32 v66, v68, v69
	v_exp_f32_e32 v72, v72
	v_exp_f32_e32 v73, v73
	v_add_f32_e32 v190, v190, v70
	v_mfma_f32_32x32x16_bf16 v[16:31], v[192:195], v[112:115], v[16:31]
	v_lshl_add_u64 v[188:189], v[188:189], 0, s[68:69]
	v_add_f32_e32 v214, v214, v71
	v_cvt_pk_bf16_f32 v67, v70, v71
	v_exp_f32_e32 v74, v74
	v_exp_f32_e32 v75, v75
	v_add_f32_e32 v190, v190, v72
	v_mfma_f32_32x32x16_bf16 v[16:31], v[242:245], v[116:119], v[16:31]
	s_and_b32 s23, s22, 3
	s_mulk_i32 s23, 0x2400
	s_xor_b32 s23, s23, 0x4800
	v_add_f32_e32 v214, v214, v73
	v_cvt_pk_bf16_f32 v68, v72, v73
	v_exp_f32_e32 v76, v76
	v_exp_f32_e32 v77, v77
	v_add_f32_e32 v190, v190, v74
	v_mfma_f32_32x32x16_bf16 v[48:63], v[242:245], v[100:103], v[48:63]
	v_add_u32_e32 v201, s23, v197
	s_add_i32 s23, s22, 2
	s_and_b32 s23, s23, 7
	s_mulk_i32 s23, 0x2400
	v_add_f32_e32 v214, v214, v75
	v_cvt_pk_bf16_f32 v69, v74, v75
	v_exp_f32_e32 v78, v78
	v_exp_f32_e32 v79, v79
	v_add_f32_e32 v190, v190, v76
	v_mfma_f32_32x32x16_bf16 v[48:63], v[192:195], v[96:99], v[48:63]
	ds_read_b128 v[202:205], v246 offset:36864
	ds_read_b128 v[192:195], v246 offset:41472
	ds_read_b128 v[210:213], v246 offset:36896
	ds_read_b128 v[242:245], v246 offset:41504
	s_waitcnt lgkmcnt(4)
	v_add_f32_e32 v214, v214, v77
	v_cvt_pk_bf16_f32 v70, v76, v77
	v_add_f32_e32 v190, v190, v78
	v_add_f32_e32 v214, v214, v79
	v_cvt_pk_bf16_f32 v71, v78, v79
	v_mfma_f32_32x32x16_bf16 v[96:111], v[226:229], v[146:149], 0
	v_add_u32_e32 v206, s23, v197
	v_exp_f32_e32 v80, v80
	v_exp_f32_e32 v81, v81
	v_exp_f32_e32 v82, v82
	v_exp_f32_e32 v83, v83
	v_add_f32_e32 v191, v191, v80
	v_mfma_f32_32x32x16_bf16 v[96:111], v[230:233], v[138:141], v[96:111]
	s_cmpk_gt_u32 s22, 0x7d
	s_cbranch_scc1 .Lc_nostore
	s_waitcnt vmcnt(0)
	ds_write_b128 v201, v[130:133]
	ds_write_b128 v206, v[134:137] offset:36864
.Lc_nostore:
	v_add_f32_e32 v215, v215, v81
	v_cvt_pk_bf16_f32 v80, v80, v81
	v_exp_f32_e32 v84, v84
	v_exp_f32_e32 v85, v85
	v_add_f32_e32 v191, v191, v82
	v_mfma_f32_32x32x16_bf16 v[96:111], v[234:237], v[142:145], v[96:111]
	v_add_f32_e32 v215, v215, v83
	v_cvt_pk_bf16_f32 v81, v82, v83
	v_exp_f32_e32 v86, v86
	v_exp_f32_e32 v87, v87
	v_add_f32_e32 v191, v191, v84
	v_mfma_f32_32x32x16_bf16 v[96:111], v[238:241], v[150:153], v[96:111]
	v_add_f32_e32 v215, v215, v85
	v_cvt_pk_bf16_f32 v82, v84, v85
	v_exp_f32_e32 v88, v88
	v_exp_f32_e32 v89, v89
	v_add_f32_e32 v191, v191, v86
	v_mfma_f32_32x32x16_bf16 v[112:127], v[238:241], v[166:169], 0
	s_add_i32 s23, s22, 1
	s_and_b32 s23, s23, 3
	s_mulk_i32 s23, 0x2400
	v_add_f32_e32 v215, v215, v87
	v_cvt_pk_bf16_f32 v83, v86, v87
	v_exp_f32_e32 v90, v90
	v_exp_f32_e32 v91, v91
	v_add_f32_e32 v191, v191, v88
	v_mfma_f32_32x32x16_bf16 v[112:127], v[234:237], v[162:165], v[112:127]
	v_add_u32_e32 v128, s23, v198
	v_add_f32_e32 v215, v215, v89
	v_cvt_pk_bf16_f32 v84, v88, v89
	v_exp_f32_e32 v92, v92
	v_exp_f32_e32 v93, v93
	v_add_f32_e32 v191, v191, v90
	v_mfma_f32_32x32x16_bf16 v[112:127], v[230:233], v[158:161], v[112:127]
	v_add_f32_e32 v215, v215, v91
	v_cvt_pk_bf16_f32 v85, v90, v91
	v_exp_f32_e32 v94, v94
	v_exp_f32_e32 v95, v95
	v_add_f32_e32 v191, v191, v92
	v_mfma_f32_32x32x16_bf16 v[112:127], v[226:229], v[154:157], v[112:127]
	v_add_f32_e32 v215, v215, v93
	v_cvt_pk_bf16_f32 v86, v92, v93
	v_add_f32_e32 v191, v191, v94
	v_add_f32_e32 v215, v215, v95
	v_cvt_pk_bf16_f32 v87, v94, v95
	s_bitcmp0_b32 s22, 0
	s_cbranch_scc1 .Lc_nobar
	s_waitcnt lgkmcnt(0)
	s_barrier
; __device__ __forceinline__ void attn_c_unit(LAS unsigned char* lds, const bf16_t* proj, const bf16_t* vt, bf16_t* obuf, int b, int hk, int blk, float mref, unsigned long long* sg) {
;     ...
;     for (int it = 0; it < nT; ++it) {
;         const int buf = it & 3;
;         if (it + 2 < nT) { kreg = *(const u32x4*)(kg + (size_t)((it + 2) * 64) * INW); vreg = *(const u32x4*)(vg + (it + 2) * 64); }
;         const LAS unsigned char* kb = lds + CK + buf * ATT_TILE + pr * KP + 16 * h;
;         f32x16 s00, s01, s10, s11;
;         {
;             const bf16x8 a0 = *(const LAS bf16x8*)(kb), a1 = *(const LAS bf16x8*)(kb + 32 * KP);
;             s00 = __builtin_amdgcn_mfma_f32_32x32x16_bf16(a0, qf[0][0], negm, 0, 0, 0);
;             s10 = __builtin_amdgcn_mfma_f32_32x32x16_bf16(a0, qf[1][0], negm, 0, 0, 0);
;             s01 = __builtin_amdgcn_mfma_f32_32x32x16_bf16(a1, qf[0][0], negm, 0, 0, 0);
;             s11 = __builtin_amdgcn_mfma_f32_32x32x16_bf16(a1, qf[1][0], negm, 0, 0, 0);
;         }
; #pragma unroll
;         for (int ks = 1; ks < 4; ++ks) {
;             const bf16x8 a0 = *(const LAS bf16x8*)(kb + 32 * ks), a1 = *(const LAS bf16x8*)(kb + 32 * KP + 32 * ks);
;             s00 = __builtin_amdgcn_mfma_f32_32x32x16_bf16(a0, qf[0][ks], s00, 0, 0, 0);
;             s10 = __builtin_amdgcn_mfma_f32_32x32x16_bf16(a0, qf[1][ks], s10, 0, 0, 0);
;             s01 = __builtin_amdgcn_mfma_f32_32x32x16_bf16(a1, qf[0][ks], s01, 0, 0, 0);
;             s11 = __builtin_amdgcn_mfma_f32_32x32x16_bf16(a1, qf[1][ks], s11, 0, 0, 0);
;         }
;         u32x4 pw0[4], pw1[4];
;         {
;             float ps = 0.f;
; #pragma unroll
;             for (int i = 0; i < 16; ++i) { s00[i] = __builtin_amdgcn_exp2f(s00[i]); s01[i] = __builtin_amdgcn_exp2f(s01[i]); ps += s00[i] + s01[i]; }
;             l0 += ps;
; #pragma unroll
;             for (int q = 0; q < 4; ++q) { pw0[0][q] = pk_bf16(s00[2 * q], s00[2 * q + 1]); pw0[1][q] = pk_bf16(s00[8 + 2 * q], s00[8 + 2 * q + 1]);
;                                           pw0[2][q] = pk_bf16(s01[2 * q], s01[2 * q + 1]); pw0[3][q] = pk_bf16(s01[8 + 2 * q], s01[8 + 2 * q + 1]); }
;         }
;         {
;             float ps = 0.f;
; #pragma unroll
;             for (int i = 0; i < 16; ++i) { s10[i] = __builtin_amdgcn_exp2f(s10[i]); s11[i] = __builtin_amdgcn_exp2f(s11[i]); ps += s10[i] + s11[i]; }
;             l1 += ps;
; #pragma unroll
.Lc_nobar:
	s_waitcnt lgkmcnt(0)
	v_mfma_f32_32x32x16_bf16 v[32:47], v[202:205], v[64:67], v[32:47]
	ds_read_b128 v[226:229], v128 offset:0
	ds_read_b128 v[230:233], v128 offset:32
	v_exp_f32_e32 v96, v96
	v_exp_f32_e32 v97, v97
	v_exp_f32_e32 v98, v98
	v_exp_f32_e32 v99, v99
	v_add_f32_e32 v190, v190, v96
	v_mfma_f32_32x32x16_bf16 v[32:47], v[210:213], v[68:71], v[32:47]
	ds_read_b128 v[234:237], v128 offset:64
	ds_read_b128 v[238:241], v128 offset:96
	v_add_f32_e32 v214, v214, v97
	v_cvt_pk_bf16_f32 v96, v96, v97
	v_exp_f32_e32 v100, v100
	v_exp_f32_e32 v101, v101
	v_add_f32_e32 v190, v190, v98
	v_mfma_f32_32x32x16_bf16 v[0:15], v[210:213], v[84:87], v[0:15]
	v_add_f32_e32 v214, v214, v99
	v_cvt_pk_bf16_f32 v97, v98, v99
	v_exp_f32_e32 v102, v102
	v_exp_f32_e32 v103, v103
	v_add_f32_e32 v190, v190, v100
	v_mfma_f32_32x32x16_bf16 v[0:15], v[202:205], v[80:83], v[0:15]
	v_add_f32_e32 v214, v214, v101
	v_cvt_pk_bf16_f32 v98, v100, v101
	v_exp_f32_e32 v104, v104
	v_exp_f32_e32 v105, v105
	v_add_f32_e32 v190, v190, v102
	v_mfma_f32_32x32x16_bf16 v[16:31], v[192:195], v[80:83], v[16:31]
	v_add_f32_e32 v214, v214, v103
	v_cvt_pk_bf16_f32 v99, v102, v103
	v_exp_f32_e32 v106, v106
	v_exp_f32_e32 v107, v107
	v_add_f32_e32 v190, v190, v104
	v_mfma_f32_32x32x16_bf16 v[16:31], v[242:245], v[84:87], v[16:31]
	v_add_f32_e32 v214, v214, v105
	v_cvt_pk_bf16_f32 v100, v104, v105
	v_exp_f32_e32 v108, v108
	v_exp_f32_e32 v109, v109
	v_add_f32_e32 v190, v190, v106
	v_mfma_f32_32x32x16_bf16 v[48:63], v[242:245], v[68:71], v[48:63]
	v_add_f32_e32 v214, v214, v107
	v_cvt_pk_bf16_f32 v101, v106, v107
	v_exp_f32_e32 v110, v110
	v_exp_f32_e32 v111, v111
	v_add_f32_e32 v190, v190, v108
	v_mfma_f32_32x32x16_bf16 v[48:63], v[192:195], v[64:67], v[48:63]
	ds_read_b128 v[202:205], v246 offset:36928
	ds_read_b128 v[192:195], v246 offset:41536
	ds_read_b128 v[210:213], v246 offset:36960
	ds_read_b128 v[242:245], v246 offset:41568
	s_waitcnt lgkmcnt(4)
	v_add_f32_e32 v214, v214, v109
	v_cvt_pk_bf16_f32 v102, v108, v109
	v_add_f32_e32 v190, v190, v110
	v_add_f32_e32 v214, v214, v111
	v_cvt_pk_bf16_f32 v103, v110, v111
	v_mfma_f32_32x32x16_bf16 v[64:79], v[226:229], v[146:149], 0
	v_exp_f32_e32 v112, v112
	v_exp_f32_e32 v113, v113
	v_exp_f32_e32 v114, v114
	v_exp_f32_e32 v115, v115
	v_add_f32_e32 v191, v191, v112
	v_mfma_f32_32x32x16_bf16 v[64:79], v[230:233], v[138:141], v[64:79]
	v_add_f32_e32 v215, v215, v113
	v_cvt_pk_bf16_f32 v112, v112, v113
	v_exp_f32_e32 v116, v116
	v_exp_f32_e32 v117, v117
	v_add_f32_e32 v191, v191, v114
	v_mfma_f32_32x32x16_bf16 v[64:79], v[234:237], v[142:145], v[64:79]
	s_add_i32 s22, s22, 1
	v_add_f32_e32 v215, v215, v115
	v_cvt_pk_bf16_f32 v113, v114, v115
	v_exp_f32_e32 v118, v118
	v_exp_f32_e32 v119, v119
	v_add_f32_e32 v191, v191, v116
	v_mfma_f32_32x32x16_bf16 v[64:79], v[238:241], v[150:153], v[64:79]
	v_add_f32_e32 v215, v215, v117
	v_cvt_pk_bf16_f32 v114, v116, v117
	v_exp_f32_e32 v120, v120
	v_exp_f32_e32 v121, v121
	v_add_f32_e32 v191, v191, v118
	v_mfma_f32_32x32x16_bf16 v[80:95], v[238:241], v[166:169], 0
	ds_read_b128 v[238:241], v128 offset:4704
	v_add_f32_e32 v215, v215, v119
	v_cvt_pk_bf16_f32 v115, v118, v119
	v_exp_f32_e32 v122, v122
	v_exp_f32_e32 v123, v123
	v_add_f32_e32 v191, v191, v120
	v_mfma_f32_32x32x16_bf16 v[80:95], v[234:237], v[162:165], v[80:95]
	ds_read_b128 v[234:237], v128 offset:4672
	v_add_f32_e32 v215, v215, v121
	v_cvt_pk_bf16_f32 v116, v120, v121
	v_exp_f32_e32 v124, v124
	v_exp_f32_e32 v125, v125
	v_add_f32_e32 v191, v191, v122
	v_mfma_f32_32x32x16_bf16 v[80:95], v[230:233], v[158:161], v[80:95]
	ds_read_b128 v[230:233], v128 offset:4640
	v_add_f32_e32 v215, v215, v123
	v_cvt_pk_bf16_f32 v117, v122, v123
	v_exp_f32_e32 v126, v126
	v_exp_f32_e32 v127, v127
	v_add_f32_e32 v191, v191, v124
	v_mfma_f32_32x32x16_bf16 v[80:95], v[226:229], v[154:157], v[80:95]
	ds_read_b128 v[226:229], v128 offset:4608
	v_add_f32_e32 v215, v215, v125
	v_cvt_pk_bf16_f32 v118, v124, v125
	v_add_f32_e32 v191, v191, v126
	v_add_f32_e32 v215, v215, v127
	v_cvt_pk_bf16_f32 v119, v126, v127
	s_cmpk_eq_i32 s22, 0x80
	s_cbranch_scc0 .Lc_top
	s_waitcnt lgkmcnt(0)
	v_mfma_f32_32x32x16_bf16 v[32:47], v[202:205], v[96:99], v[32:47]
	v_mfma_f32_32x32x16_bf16 v[32:47], v[210:213], v[100:103], v[32:47]
	v_mfma_f32_32x32x16_bf16 v[0:15], v[210:213], v[116:119], v[0:15]
	v_mfma_f32_32x32x16_bf16 v[0:15], v[202:205], v[112:115], v[0:15]
	v_mfma_f32_32x32x16_bf16 v[16:31], v[192:195], v[112:115], v[16:31]
	v_mfma_f32_32x32x16_bf16 v[16:31], v[242:245], v[116:119], v[16:31]
	v_mfma_f32_32x32x16_bf16 v[48:63], v[242:245], v[100:103], v[48:63]
	v_mfma_f32_32x32x16_bf16 v[48:63], v[192:195], v[96:99], v[48:63]
	v_add_f32_e32 v190, v190, v214
	v_add_f32_e32 v191, v191, v215
	s_barrier
